# pass-2 tails compare the f32 score against per-query float thresholds (exact inverse of the bin map) instead of computing the bin; head sums in 2-pair blocks
# speedup vs baseline: 1.0441x; 1.0036x over previous
.LBB0_1024:
	v_mov_b32_e32 v246, v149
	v_add_u32_e32 v247, 0x471, v246
	v_lshlrev_b32_e32 v247, 19, v247
	v_sub_u32_e32 v248, 0x86f, v246
	v_lshlrev_b32_e32 v248, 19, v248
	v_add_u32_e32 v248, 0x7fffffff, v248
	v_cmp_lt_i32_e32 vcc, 0x1ff, v246
	s_nop 1
	v_cndmask_b32_e32 v250, v248, v247, vcc
	v_cmp_ne_u32_e32 vcc, 0x1ff, v246
	s_nop 1
	v_cndmask_b32_e32 v250, 0, v250, vcc
	v_cmp_ne_u32_e32 vcc, 0x3ff, v246
	v_mov_b32_e32 v249, 0x7fc00000
	s_nop 0
	v_cndmask_b32_e32 v250, v249, v250, vcc
	v_cmp_le_i32_e32 vcc, 0, v246
	s_nop 1
	v_mov_b32_e32 v249, s33
	v_cndmask_b32_e32 v250, v249, v250, vcc
	v_add_u32_e32 v246, -1, v149
	v_add_u32_e32 v247, 0x471, v246
	v_lshlrev_b32_e32 v247, 19, v247
	v_sub_u32_e32 v248, 0x86f, v246
	v_lshlrev_b32_e32 v248, 19, v248
	v_add_u32_e32 v248, 0x7fffffff, v248
	v_cmp_lt_i32_e32 vcc, 0x1ff, v246
	s_nop 1
	v_cndmask_b32_e32 v156, v248, v247, vcc
	v_cmp_ne_u32_e32 vcc, 0x1ff, v246
	s_nop 1
	v_cndmask_b32_e32 v156, 0, v156, vcc
	v_cmp_ne_u32_e32 vcc, 0x3ff, v246
	v_mov_b32_e32 v249, 0x7fc00000
	s_nop 0
	v_cndmask_b32_e32 v156, v249, v156, vcc
	v_cmp_le_i32_e32 vcc, 0, v246
	s_nop 1
	v_mov_b32_e32 v249, s33
	v_cndmask_b32_e32 v156, v249, v156, vcc
	v_mov_b32_e32 v246, v159
	v_add_u32_e32 v247, 0x471, v246
	v_lshlrev_b32_e32 v247, 19, v247
	v_sub_u32_e32 v248, 0x86f, v246
	v_lshlrev_b32_e32 v248, 19, v248
	v_add_u32_e32 v248, 0x7fffffff, v248
	v_cmp_lt_i32_e32 vcc, 0x1ff, v246
	s_nop 1
	v_cndmask_b32_e32 v197, v248, v247, vcc
	v_cmp_ne_u32_e32 vcc, 0x1ff, v246
	s_nop 1
	v_cndmask_b32_e32 v197, 0, v197, vcc
	v_cmp_ne_u32_e32 vcc, 0x3ff, v246
	v_mov_b32_e32 v249, 0x7fc00000
	s_nop 0
	v_cndmask_b32_e32 v197, v249, v197, vcc
	v_cmp_le_i32_e32 vcc, 0, v246
	s_nop 1
	v_mov_b32_e32 v249, s33
	v_cndmask_b32_e32 v197, v249, v197, vcc
	v_add_u32_e32 v246, -1, v159
	v_add_u32_e32 v247, 0x471, v246
	v_lshlrev_b32_e32 v247, 19, v247
	v_sub_u32_e32 v248, 0x86f, v246
	v_lshlrev_b32_e32 v248, 19, v248
	v_add_u32_e32 v248, 0x7fffffff, v248
	v_cmp_lt_i32_e32 vcc, 0x1ff, v246
	s_nop 1
	v_cndmask_b32_e32 v157, v248, v247, vcc
	v_cmp_ne_u32_e32 vcc, 0x1ff, v246
	s_nop 1
	v_cndmask_b32_e32 v157, 0, v157, vcc
	v_cmp_ne_u32_e32 vcc, 0x3ff, v246
	v_mov_b32_e32 v249, 0x7fc00000
	s_nop 0
	v_cndmask_b32_e32 v157, v249, v157, vcc
	v_cmp_le_i32_e32 vcc, 0, v246
	s_nop 1
	v_mov_b32_e32 v249, s33
	v_cndmask_b32_e32 v157, v249, v157, vcc
	ds_read_b128 v[164:167], v99 offset:0
	ds_read_b128 v[168:171], v99 offset:4096
	ds_read_b128 v[172:175], v99 offset:1024
	ds_read_b128 v[176:179], v99 offset:5120
	ds_read_b128 v[230:233], v99 offset:2048
	ds_read_b128 v[234:237], v99 offset:6144
	ds_read_b128 v[238:241], v99 offset:3072
	ds_read_b128 v[242:245], v99 offset:7168
	s_waitcnt lgkmcnt(7)
	v_mfma_f32_32x32x16_bf16 v[16:31], v[34:37], v[164:167], 0
	s_waitcnt lgkmcnt(6)
	v_mfma_f32_32x32x16_bf16 v[0:15], v[34:37], v[168:171], 0
	s_waitcnt vmcnt(3)
	ds_write_b128 v140, v[50:53] offset:8192
	s_add_i32 s4, s18, 5
	s_min_i32 s4, s4, s14
	v_mad_i64_i32 v[164:165], s[4:5], s4, v193, v[116:117]
	global_load_dwordx4 v[50:53], v[164:165], off
	s_waitcnt lgkmcnt(6)
	v_mfma_f32_32x32x16_bf16 v[16:31], v[38:41], v[172:175], v[16:31]
	s_waitcnt lgkmcnt(5)
	v_mfma_f32_32x32x16_bf16 v[0:15], v[38:41], v[176:179], v[0:15]
	s_waitcnt lgkmcnt(4)
	v_mfma_f32_32x32x16_bf16 v[16:31], v[42:45], v[230:233], v[16:31]
	s_waitcnt lgkmcnt(3)
	v_mfma_f32_32x32x16_bf16 v[0:15], v[42:45], v[234:237], v[0:15]
	s_waitcnt lgkmcnt(2)
	v_mfma_f32_32x32x16_bf16 v[16:31], v[46:49], v[238:241], v[16:31]
	s_waitcnt lgkmcnt(1)
	v_mfma_f32_32x32x16_bf16 v[0:15], v[46:49], v[242:245], v[0:15]
	s_waitcnt lgkmcnt(0)
	s_barrier
	s_add_u32 s18, s18, 1
	s_cmp_ge_u32 s18, s13
	s_cbranch_scc1 .Lp2_drain0
.Lp2_c1:
	ds_read_b128 v[164:167], v99 offset:8192
	ds_read_b128 v[168:171], v99 offset:12288
	ds_read_b128 v[172:175], v99 offset:9216
	ds_read_b128 v[176:179], v99 offset:13312
	ds_read_b128 v[230:233], v99 offset:10240
	ds_read_b128 v[234:237], v99 offset:14336
	ds_read_b128 v[238:241], v99 offset:11264
	ds_read_b128 v[242:245], v99 offset:15360
	v_max_i32_e32 v246, 0, v24
	v_max_i32_e32 v247, 0, v16
	v_max_i32_e32 v248, 0, v25
	v_max_i32_e32 v249, 0, v17
	s_waitcnt lgkmcnt(7)
	v_mfma_f32_32x32x16_bf16 v[198:213], v[34:37], v[164:167], 0
	v_pk_fma_f32 v[184:185], v[100:101], v[246:247], 0 op_sel_hi:[1,1,0]
	v_pk_fma_f32 v[184:185], v[102:103], v[248:249], v[184:185]
	v_max_i32_e32 v246, 0, v26
	v_max_i32_e32 v247, 0, v18
	v_max_i32_e32 v248, 0, v27
	v_max_i32_e32 v249, 0, v19
	v_pk_fma_f32 v[184:185], v[104:105], v[246:247], v[184:185]
	v_pk_fma_f32 v[184:185], v[106:107], v[248:249], v[184:185]
	s_waitcnt lgkmcnt(6)
	v_mfma_f32_32x32x16_bf16 v[214:229], v[34:37], v[168:171], 0
	s_waitcnt vmcnt(3)
	ds_write_b128 v140, v[54:57]
	s_add_i32 s4, s18, 5
	s_min_i32 s4, s4, s14
	v_mad_i64_i32 v[164:165], s[4:5], s4, v193, v[116:117]
	global_load_dwordx4 v[54:57], v[164:165], off
	v_max_i32_e32 v246, 0, v28
	v_max_i32_e32 v247, 0, v20
	v_max_i32_e32 v248, 0, v29
	v_max_i32_e32 v249, 0, v21
	v_pk_fma_f32 v[184:185], v[108:109], v[246:247], v[184:185]
	v_pk_fma_f32 v[184:185], v[110:111], v[248:249], v[184:185]
	v_max_i32_e32 v246, 0, v30
	v_max_i32_e32 v247, 0, v22
	s_waitcnt lgkmcnt(6)
	v_mfma_f32_32x32x16_bf16 v[198:213], v[38:41], v[172:175], v[198:213]
	v_max_i32_e32 v248, 0, v31
	v_max_i32_e32 v249, 0, v23
	v_pk_fma_f32 v[184:185], v[112:113], v[246:247], v[184:185]
	v_pk_fma_f32 v[184:185], v[114:115], v[248:249], v[184:185]
	s_waitcnt lgkmcnt(5)
	v_mfma_f32_32x32x16_bf16 v[214:229], v[38:41], v[176:179], v[214:229]
	v_cmp_le_f32_e32 vcc, v250, v185
	s_mov_b64 s[52:53], vcc
	s_and_saveexec_b64 s[4:5], s[50:51]
	v_mov_b32_e32 v246, vcc_hi
	v_mov_b32_e32 v247, vcc_lo
	v_cndmask_b32_e64 v246, v246, v247, s[48:49]
	ds_write_b32 v162, v246
	s_or_b64 exec, exec, s[4:5]
	v_cmp_le_f32_e32 vcc, v156, v185
	s_andn2_b64 vcc, vcc, s[52:53]
	s_cbranch_vccz .Lp2_skip1
	v_mov_b32_e32 v246, vcc_hi
	v_mov_b32_e32 v247, vcc_lo
	v_cndmask_b32_e64 v246, v246, v247, s[48:49]
	s_and_saveexec_b64 s[4:5], vcc
	s_cbranch_execz .Lp2_join1
	v_and_b32_e32 v247, v246, v127
	v_bcnt_u32_b32 v247, v247, v119
	v_cmp_gt_u32_e32 vcc, s35, v247
	s_and_b64 exec, exec, vcc
	s_cbranch_execz .Lp2_join1
	v_cmp_gt_f32_e64 s[52:53], 0, v185
	v_not_b32_e32 v248, v185
	s_nop 0
	v_cndmask_b32_e64 v33, -|v185|, v248, s[52:53]
	v_lshl_add_u64 v[154:155], v[78:79], 0, s[0:1]
	v_lshl_add_u64 v[154:155], v[154:155], 0, v[32:33]
	v_lshl_add_u32 v248, v247, 3, v160
	ds_write_b64 v248, v[154:155] offset:2048

.Lp2_skip1:
	s_waitcnt lgkmcnt(5)
	v_mfma_f32_32x32x16_bf16 v[198:213], v[42:45], v[230:233], v[198:213]
	v_cmp_le_f32_e32 vcc, v197, v184
	s_mov_b64 s[52:53], vcc
	s_and_saveexec_b64 s[4:5], s[50:51]
	v_mov_b32_e32 v246, vcc_hi
	v_mov_b32_e32 v247, vcc_lo
	v_cndmask_b32_e64 v246, v246, v247, s[48:49]
	ds_write_b32 v162, v246 offset:1024
	s_or_b64 exec, exec, s[4:5]
	v_cmp_le_f32_e32 vcc, v157, v184
	s_andn2_b64 vcc, vcc, s[52:53]
	s_cbranch_vccz .Lp2_skip2
	v_mov_b32_e32 v246, vcc_hi
	v_mov_b32_e32 v247, vcc_lo
	v_cndmask_b32_e64 v246, v246, v247, s[48:49]
	s_and_saveexec_b64 s[4:5], vcc
	s_cbranch_execz .Lp2_join2
	v_and_b32_e32 v247, v246, v127
	v_bcnt_u32_b32 v247, v247, v118
	v_cmp_gt_u32_e32 vcc, s35, v247
	s_and_b64 exec, exec, vcc
	s_cbranch_execz .Lp2_join2
	v_cmp_gt_f32_e64 s[52:53], 0, v184
	v_not_b32_e32 v248, v184
	s_nop 0
	v_cndmask_b32_e64 v33, -|v184|, v248, s[52:53]
	v_lshl_add_u64 v[154:155], v[78:79], 0, s[0:1]
	v_lshl_add_u64 v[154:155], v[154:155], 0, v[32:33]
	v_lshl_add_u32 v248, v247, 3, v161
	ds_write_b64 v248, v[154:155] offset:2048

.Lp2_skip2:
	v_max_i32_e32 v246, 0, v8
	v_max_i32_e32 v247, 0, v0
	s_waitcnt lgkmcnt(5)
	v_mfma_f32_32x32x16_bf16 v[214:229], v[42:45], v[234:237], v[214:229]
	v_max_i32_e32 v248, 0, v9
	v_max_i32_e32 v249, 0, v1
	v_pk_fma_f32 v[184:185], v[100:101], v[246:247], 0 op_sel_hi:[1,1,0]
	v_pk_fma_f32 v[184:185], v[102:103], v[248:249], v[184:185]
	v_max_i32_e32 v246, 0, v10
	v_max_i32_e32 v247, 0, v2
	v_max_i32_e32 v248, 0, v11
	v_max_i32_e32 v249, 0, v3
	s_waitcnt lgkmcnt(4)
	v_mfma_f32_32x32x16_bf16 v[198:213], v[46:49], v[238:241], v[198:213]
	v_pk_fma_f32 v[184:185], v[104:105], v[246:247], v[184:185]
	v_pk_fma_f32 v[184:185], v[106:107], v[248:249], v[184:185]
	v_max_i32_e32 v246, 0, v12
	v_max_i32_e32 v247, 0, v4
	v_max_i32_e32 v248, 0, v13
	v_max_i32_e32 v249, 0, v5
	v_pk_fma_f32 v[184:185], v[108:109], v[246:247], v[184:185]
	v_pk_fma_f32 v[184:185], v[110:111], v[248:249], v[184:185]
	s_waitcnt lgkmcnt(3)
	v_mfma_f32_32x32x16_bf16 v[214:229], v[46:49], v[242:245], v[214:229]
	v_max_i32_e32 v246, 0, v14
	v_max_i32_e32 v247, 0, v6
	v_max_i32_e32 v248, 0, v15
	v_max_i32_e32 v249, 0, v7
	v_pk_fma_f32 v[184:185], v[112:113], v[246:247], v[184:185]
	v_pk_fma_f32 v[184:185], v[114:115], v[248:249], v[184:185]
	v_cmp_le_f32_e32 vcc, v250, v185
	s_mov_b64 s[52:53], vcc
	s_and_saveexec_b64 s[4:5], s[50:51]
	v_mov_b32_e32 v246, vcc_hi
	v_mov_b32_e32 v247, vcc_lo
	v_cndmask_b32_e64 v246, v246, v247, s[48:49]
	ds_write_b32 v162, v246 offset:4
	s_or_b64 exec, exec, s[4:5]
	v_cmp_le_f32_e32 vcc, v156, v185
	s_andn2_b64 vcc, vcc, s[52:53]
	s_cbranch_vccz .Lp2_skip3
	v_mov_b32_e32 v246, vcc_hi
	v_mov_b32_e32 v247, vcc_lo
	v_cndmask_b32_e64 v246, v246, v247, s[48:49]
	s_and_saveexec_b64 s[4:5], vcc
	s_cbranch_execz .Lp2_join3
	v_and_b32_e32 v247, v246, v127
	v_bcnt_u32_b32 v247, v247, v119
	v_cmp_gt_u32_e32 vcc, s35, v247
	s_and_b64 exec, exec, vcc
	s_cbranch_execz .Lp2_join3
	v_cmp_gt_f32_e64 s[52:53], 0, v185
	v_not_b32_e32 v248, v185
	s_nop 0
	v_cndmask_b32_e64 v33, -|v185|, v248, s[52:53]
	v_lshl_add_u64 v[154:155], v[96:97], 0, s[0:1]
	v_lshl_add_u64 v[154:155], v[154:155], 0, v[32:33]
	v_lshl_add_u32 v248, v247, 3, v160
	ds_write_b64 v248, v[154:155] offset:2048

.Lp2_skip3:
	v_cmp_le_f32_e32 vcc, v197, v184
	s_mov_b64 s[52:53], vcc
	s_and_saveexec_b64 s[4:5], s[50:51]
	v_mov_b32_e32 v246, vcc_hi
	v_mov_b32_e32 v247, vcc_lo
	v_cndmask_b32_e64 v246, v246, v247, s[48:49]
	ds_write_b32 v162, v246 offset:1028
	s_or_b64 exec, exec, s[4:5]
	v_cmp_le_f32_e32 vcc, v157, v184
	s_andn2_b64 vcc, vcc, s[52:53]
	s_cbranch_vccz .Lp2_skip4
	v_mov_b32_e32 v246, vcc_hi
	v_mov_b32_e32 v247, vcc_lo
	v_cndmask_b32_e64 v246, v246, v247, s[48:49]
	s_and_saveexec_b64 s[4:5], vcc
	s_cbranch_execz .Lp2_join4
	v_and_b32_e32 v247, v246, v127
	v_bcnt_u32_b32 v247, v247, v118
	v_cmp_gt_u32_e32 vcc, s35, v247
	s_and_b64 exec, exec, vcc
	s_cbranch_execz .Lp2_join4
	v_cmp_gt_f32_e64 s[52:53], 0, v184
	v_not_b32_e32 v248, v184
	s_nop 0
	v_cndmask_b32_e64 v33, -|v184|, v248, s[52:53]
	v_lshl_add_u64 v[154:155], v[96:97], 0, s[0:1]
	v_lshl_add_u64 v[154:155], v[154:155], 0, v[32:33]
	v_lshl_add_u32 v248, v247, 3, v161
	ds_write_b64 v248, v[154:155] offset:2048

.Lp2_c2:
	ds_read_b128 v[164:167], v99 offset:0
	ds_read_b128 v[168:171], v99 offset:4096
	ds_read_b128 v[172:175], v99 offset:1024
	ds_read_b128 v[176:179], v99 offset:5120
	ds_read_b128 v[230:233], v99 offset:2048
	ds_read_b128 v[234:237], v99 offset:6144
	ds_read_b128 v[238:241], v99 offset:3072
	ds_read_b128 v[242:245], v99 offset:7168
	v_max_i32_e32 v246, 0, v206
	v_max_i32_e32 v247, 0, v198
	v_max_i32_e32 v248, 0, v207
	v_max_i32_e32 v249, 0, v199
	s_waitcnt lgkmcnt(7)
	v_mfma_f32_32x32x16_bf16 v[16:31], v[34:37], v[164:167], 0
	v_pk_fma_f32 v[184:185], v[100:101], v[246:247], 0 op_sel_hi:[1,1,0]
	v_pk_fma_f32 v[184:185], v[102:103], v[248:249], v[184:185]
	v_max_i32_e32 v246, 0, v208
	v_max_i32_e32 v247, 0, v200
	v_max_i32_e32 v248, 0, v209
	v_max_i32_e32 v249, 0, v201
	v_pk_fma_f32 v[184:185], v[104:105], v[246:247], v[184:185]
	v_pk_fma_f32 v[184:185], v[106:107], v[248:249], v[184:185]
	s_waitcnt lgkmcnt(6)
	v_mfma_f32_32x32x16_bf16 v[0:15], v[34:37], v[168:171], 0
	s_waitcnt vmcnt(3)
	ds_write_b128 v140, v[58:61] offset:8192
	s_add_i32 s4, s18, 5
	s_min_i32 s4, s4, s14
	v_mad_i64_i32 v[164:165], s[4:5], s4, v193, v[116:117]
	global_load_dwordx4 v[58:61], v[164:165], off
	v_max_i32_e32 v246, 0, v210
	v_max_i32_e32 v247, 0, v202
	v_max_i32_e32 v248, 0, v211
	v_max_i32_e32 v249, 0, v203
	v_pk_fma_f32 v[184:185], v[108:109], v[246:247], v[184:185]
	v_pk_fma_f32 v[184:185], v[110:111], v[248:249], v[184:185]
	v_max_i32_e32 v246, 0, v212
	v_max_i32_e32 v247, 0, v204
	s_waitcnt lgkmcnt(6)
	v_mfma_f32_32x32x16_bf16 v[16:31], v[38:41], v[172:175], v[16:31]
	v_max_i32_e32 v248, 0, v213
	v_max_i32_e32 v249, 0, v205
	v_pk_fma_f32 v[184:185], v[112:113], v[246:247], v[184:185]
	v_pk_fma_f32 v[184:185], v[114:115], v[248:249], v[184:185]
	s_waitcnt lgkmcnt(5)
	v_mfma_f32_32x32x16_bf16 v[0:15], v[38:41], v[176:179], v[0:15]
	v_cmp_le_f32_e32 vcc, v250, v185
	s_mov_b64 s[52:53], vcc
	s_and_saveexec_b64 s[4:5], s[50:51]
	v_mov_b32_e32 v246, vcc_hi
	v_mov_b32_e32 v247, vcc_lo
	v_cndmask_b32_e64 v246, v246, v247, s[48:49]
	ds_write_b32 v162, v246 offset:8
	s_or_b64 exec, exec, s[4:5]
	v_cmp_le_f32_e32 vcc, v156, v185
	s_andn2_b64 vcc, vcc, s[52:53]
	s_cbranch_vccz .Lp2_skip5
	v_mov_b32_e32 v246, vcc_hi
	v_mov_b32_e32 v247, vcc_lo
	v_cndmask_b32_e64 v246, v246, v247, s[48:49]
	s_and_saveexec_b64 s[4:5], vcc
	s_cbranch_execz .Lp2_join5
	v_and_b32_e32 v247, v246, v127
	v_bcnt_u32_b32 v247, v247, v119
	v_cmp_gt_u32_e32 vcc, s35, v247
	s_and_b64 exec, exec, vcc
	s_cbranch_execz .Lp2_join5
	v_cmp_gt_f32_e64 s[52:53], 0, v185
	v_not_b32_e32 v248, v185
	s_nop 0
	v_cndmask_b32_e64 v33, -|v185|, v248, s[52:53]
	v_lshl_add_u64 v[154:155], v[92:93], 0, s[0:1]
	v_lshl_add_u64 v[154:155], v[154:155], 0, v[32:33]
	v_lshl_add_u32 v248, v247, 3, v160
	ds_write_b64 v248, v[154:155] offset:2048

.Lp2_skip5:
	s_waitcnt lgkmcnt(5)
	v_mfma_f32_32x32x16_bf16 v[16:31], v[42:45], v[230:233], v[16:31]
	v_cmp_le_f32_e32 vcc, v197, v184
	s_mov_b64 s[52:53], vcc
	s_and_saveexec_b64 s[4:5], s[50:51]
	v_mov_b32_e32 v246, vcc_hi
	v_mov_b32_e32 v247, vcc_lo
	v_cndmask_b32_e64 v246, v246, v247, s[48:49]
	ds_write_b32 v162, v246 offset:1032
	s_or_b64 exec, exec, s[4:5]
	v_cmp_le_f32_e32 vcc, v157, v184
	s_andn2_b64 vcc, vcc, s[52:53]
	s_cbranch_vccz .Lp2_skip6
	v_mov_b32_e32 v246, vcc_hi
	v_mov_b32_e32 v247, vcc_lo
	v_cndmask_b32_e64 v246, v246, v247, s[48:49]
	s_and_saveexec_b64 s[4:5], vcc
	s_cbranch_execz .Lp2_join6
	v_and_b32_e32 v247, v246, v127
	v_bcnt_u32_b32 v247, v247, v118
	v_cmp_gt_u32_e32 vcc, s35, v247
	s_and_b64 exec, exec, vcc
	s_cbranch_execz .Lp2_join6
	v_cmp_gt_f32_e64 s[52:53], 0, v184
	v_not_b32_e32 v248, v184
	s_nop 0
	v_cndmask_b32_e64 v33, -|v184|, v248, s[52:53]
	v_lshl_add_u64 v[154:155], v[92:93], 0, s[0:1]
	v_lshl_add_u64 v[154:155], v[154:155], 0, v[32:33]
	v_lshl_add_u32 v248, v247, 3, v161
	ds_write_b64 v248, v[154:155] offset:2048

.Lp2_skip6:
	v_max_i32_e32 v246, 0, v222
	v_max_i32_e32 v247, 0, v214
	s_waitcnt lgkmcnt(5)
	v_mfma_f32_32x32x16_bf16 v[0:15], v[42:45], v[234:237], v[0:15]
	v_max_i32_e32 v248, 0, v223
	v_max_i32_e32 v249, 0, v215
	v_pk_fma_f32 v[184:185], v[100:101], v[246:247], 0 op_sel_hi:[1,1,0]
	v_pk_fma_f32 v[184:185], v[102:103], v[248:249], v[184:185]
	v_max_i32_e32 v246, 0, v224
	v_max_i32_e32 v247, 0, v216
	v_max_i32_e32 v248, 0, v225
	v_max_i32_e32 v249, 0, v217
	s_waitcnt lgkmcnt(4)
	v_mfma_f32_32x32x16_bf16 v[16:31], v[46:49], v[238:241], v[16:31]
	v_pk_fma_f32 v[184:185], v[104:105], v[246:247], v[184:185]
	v_pk_fma_f32 v[184:185], v[106:107], v[248:249], v[184:185]
	v_max_i32_e32 v246, 0, v226
	v_max_i32_e32 v247, 0, v218
	v_max_i32_e32 v248, 0, v227
	v_max_i32_e32 v249, 0, v219
	v_pk_fma_f32 v[184:185], v[108:109], v[246:247], v[184:185]
	v_pk_fma_f32 v[184:185], v[110:111], v[248:249], v[184:185]
	s_waitcnt lgkmcnt(3)
	v_mfma_f32_32x32x16_bf16 v[0:15], v[46:49], v[242:245], v[0:15]
	v_max_i32_e32 v246, 0, v228
	v_max_i32_e32 v247, 0, v220
	v_max_i32_e32 v248, 0, v229
	v_max_i32_e32 v249, 0, v221
	v_pk_fma_f32 v[184:185], v[112:113], v[246:247], v[184:185]
	v_pk_fma_f32 v[184:185], v[114:115], v[248:249], v[184:185]
	v_cmp_le_f32_e32 vcc, v250, v185
	s_mov_b64 s[52:53], vcc
	s_and_saveexec_b64 s[4:5], s[50:51]
	v_mov_b32_e32 v246, vcc_hi
	v_mov_b32_e32 v247, vcc_lo
	v_cndmask_b32_e64 v246, v246, v247, s[48:49]
	ds_write_b32 v162, v246 offset:12
	s_or_b64 exec, exec, s[4:5]
	v_cmp_le_f32_e32 vcc, v156, v185
	s_andn2_b64 vcc, vcc, s[52:53]
	s_cbranch_vccz .Lp2_skip7
	v_mov_b32_e32 v246, vcc_hi
	v_mov_b32_e32 v247, vcc_lo
	v_cndmask_b32_e64 v246, v246, v247, s[48:49]
	s_and_saveexec_b64 s[4:5], vcc
	s_cbranch_execz .Lp2_join7
	v_and_b32_e32 v247, v246, v127
	v_bcnt_u32_b32 v247, v247, v119
	v_cmp_gt_u32_e32 vcc, s35, v247
	s_and_b64 exec, exec, vcc
	s_cbranch_execz .Lp2_join7
	v_cmp_gt_f32_e64 s[52:53], 0, v185
	v_not_b32_e32 v248, v185
	s_nop 0
	v_cndmask_b32_e64 v33, -|v185|, v248, s[52:53]
	v_lshl_add_u64 v[154:155], v[94:95], 0, s[0:1]
	v_lshl_add_u64 v[154:155], v[154:155], 0, v[32:33]
	v_lshl_add_u32 v248, v247, 3, v160
	ds_write_b64 v248, v[154:155] offset:2048

.Lp2_skip7:
	v_cmp_le_f32_e32 vcc, v197, v184
	s_mov_b64 s[52:53], vcc
	s_and_saveexec_b64 s[4:5], s[50:51]
	v_mov_b32_e32 v246, vcc_hi
	v_mov_b32_e32 v247, vcc_lo
	v_cndmask_b32_e64 v246, v246, v247, s[48:49]
	ds_write_b32 v162, v246 offset:1036
	s_or_b64 exec, exec, s[4:5]
	v_cmp_le_f32_e32 vcc, v157, v184
	s_andn2_b64 vcc, vcc, s[52:53]
	s_cbranch_vccz .Lp2_skip8
	v_mov_b32_e32 v246, vcc_hi
	v_mov_b32_e32 v247, vcc_lo
	v_cndmask_b32_e64 v246, v246, v247, s[48:49]
	s_and_saveexec_b64 s[4:5], vcc
	s_cbranch_execz .Lp2_join8
	v_and_b32_e32 v247, v246, v127
	v_bcnt_u32_b32 v247, v247, v118
	v_cmp_gt_u32_e32 vcc, s35, v247
	s_and_b64 exec, exec, vcc
	s_cbranch_execz .Lp2_join8
	v_cmp_gt_f32_e64 s[52:53], 0, v184
	v_not_b32_e32 v248, v184
	s_nop 0
	v_cndmask_b32_e64 v33, -|v184|, v248, s[52:53]
	v_lshl_add_u64 v[154:155], v[94:95], 0, s[0:1]
	v_lshl_add_u64 v[154:155], v[154:155], 0, v[32:33]
	v_lshl_add_u32 v248, v247, 3, v161
	ds_write_b64 v248, v[154:155] offset:2048

.Lp2_c3:
	ds_read_b128 v[164:167], v99 offset:8192
	ds_read_b128 v[168:171], v99 offset:12288
	ds_read_b128 v[172:175], v99 offset:9216
	ds_read_b128 v[176:179], v99 offset:13312
	ds_read_b128 v[230:233], v99 offset:10240
	ds_read_b128 v[234:237], v99 offset:14336
	ds_read_b128 v[238:241], v99 offset:11264
	ds_read_b128 v[242:245], v99 offset:15360
	v_max_i32_e32 v246, 0, v24
	v_max_i32_e32 v247, 0, v16
	v_max_i32_e32 v248, 0, v25
	v_max_i32_e32 v249, 0, v17
	s_waitcnt lgkmcnt(7)
	v_mfma_f32_32x32x16_bf16 v[198:213], v[34:37], v[164:167], 0
	v_pk_fma_f32 v[184:185], v[100:101], v[246:247], 0 op_sel_hi:[1,1,0]
	v_pk_fma_f32 v[184:185], v[102:103], v[248:249], v[184:185]
	v_max_i32_e32 v246, 0, v26
	v_max_i32_e32 v247, 0, v18
	v_max_i32_e32 v248, 0, v27
	v_max_i32_e32 v249, 0, v19
	v_pk_fma_f32 v[184:185], v[104:105], v[246:247], v[184:185]
	v_pk_fma_f32 v[184:185], v[106:107], v[248:249], v[184:185]
	s_waitcnt lgkmcnt(6)
	v_mfma_f32_32x32x16_bf16 v[214:229], v[34:37], v[168:171], 0
	s_waitcnt vmcnt(3)
	ds_write_b128 v140, v[62:65]
	s_add_i32 s4, s18, 5
	s_min_i32 s4, s4, s14
	v_mad_i64_i32 v[164:165], s[4:5], s4, v193, v[116:117]
	global_load_dwordx4 v[62:65], v[164:165], off
	v_max_i32_e32 v246, 0, v28
	v_max_i32_e32 v247, 0, v20
	v_max_i32_e32 v248, 0, v29
	v_max_i32_e32 v249, 0, v21
	v_pk_fma_f32 v[184:185], v[108:109], v[246:247], v[184:185]
	v_pk_fma_f32 v[184:185], v[110:111], v[248:249], v[184:185]
	v_max_i32_e32 v246, 0, v30
	v_max_i32_e32 v247, 0, v22
	s_waitcnt lgkmcnt(6)
	v_mfma_f32_32x32x16_bf16 v[198:213], v[38:41], v[172:175], v[198:213]
	v_max_i32_e32 v248, 0, v31
	v_max_i32_e32 v249, 0, v23
	v_pk_fma_f32 v[184:185], v[112:113], v[246:247], v[184:185]
	v_pk_fma_f32 v[184:185], v[114:115], v[248:249], v[184:185]
	s_waitcnt lgkmcnt(5)
	v_mfma_f32_32x32x16_bf16 v[214:229], v[38:41], v[176:179], v[214:229]
	v_cmp_le_f32_e32 vcc, v250, v185
	s_mov_b64 s[52:53], vcc
	s_and_saveexec_b64 s[4:5], s[50:51]
	v_mov_b32_e32 v246, vcc_hi
	v_mov_b32_e32 v247, vcc_lo
	v_cndmask_b32_e64 v246, v246, v247, s[48:49]
	ds_write_b32 v162, v246 offset:16
	s_or_b64 exec, exec, s[4:5]
	v_cmp_le_f32_e32 vcc, v156, v185
	s_andn2_b64 vcc, vcc, s[52:53]
	s_cbranch_vccz .Lp2_skip9
	v_mov_b32_e32 v246, vcc_hi
	v_mov_b32_e32 v247, vcc_lo
	v_cndmask_b32_e64 v246, v246, v247, s[48:49]
	s_and_saveexec_b64 s[4:5], vcc
	s_cbranch_execz .Lp2_join9
	v_and_b32_e32 v247, v246, v127
	v_bcnt_u32_b32 v247, v247, v119
	v_cmp_gt_u32_e32 vcc, s35, v247
	s_and_b64 exec, exec, vcc
	s_cbranch_execz .Lp2_join9
	v_cmp_gt_f32_e64 s[52:53], 0, v185
	v_not_b32_e32 v248, v185
	s_nop 0
	v_cndmask_b32_e64 v33, -|v185|, v248, s[52:53]
	v_lshl_add_u64 v[154:155], v[90:91], 0, s[0:1]
	v_lshl_add_u64 v[154:155], v[154:155], 0, v[32:33]
	v_lshl_add_u32 v248, v247, 3, v160
	ds_write_b64 v248, v[154:155] offset:2048

.Lp2_skip9:
	s_waitcnt lgkmcnt(5)
	v_mfma_f32_32x32x16_bf16 v[198:213], v[42:45], v[230:233], v[198:213]
	v_cmp_le_f32_e32 vcc, v197, v184
	s_mov_b64 s[52:53], vcc
	s_and_saveexec_b64 s[4:5], s[50:51]
	v_mov_b32_e32 v246, vcc_hi
	v_mov_b32_e32 v247, vcc_lo
	v_cndmask_b32_e64 v246, v246, v247, s[48:49]
	ds_write_b32 v162, v246 offset:1040
	s_or_b64 exec, exec, s[4:5]
	v_cmp_le_f32_e32 vcc, v157, v184
	s_andn2_b64 vcc, vcc, s[52:53]
	s_cbranch_vccz .Lp2_skip10
	v_mov_b32_e32 v246, vcc_hi
	v_mov_b32_e32 v247, vcc_lo
	v_cndmask_b32_e64 v246, v246, v247, s[48:49]
	s_and_saveexec_b64 s[4:5], vcc
	s_cbranch_execz .Lp2_join10
	v_and_b32_e32 v247, v246, v127
	v_bcnt_u32_b32 v247, v247, v118
	v_cmp_gt_u32_e32 vcc, s35, v247
	s_and_b64 exec, exec, vcc
	s_cbranch_execz .Lp2_join10
	v_cmp_gt_f32_e64 s[52:53], 0, v184
	v_not_b32_e32 v248, v184
	s_nop 0
	v_cndmask_b32_e64 v33, -|v184|, v248, s[52:53]
	v_lshl_add_u64 v[154:155], v[90:91], 0, s[0:1]
	v_lshl_add_u64 v[154:155], v[154:155], 0, v[32:33]
	v_lshl_add_u32 v248, v247, 3, v161
	ds_write_b64 v248, v[154:155] offset:2048

.Lp2_skip10:
	v_max_i32_e32 v246, 0, v8
	v_max_i32_e32 v247, 0, v0
	s_waitcnt lgkmcnt(5)
	v_mfma_f32_32x32x16_bf16 v[214:229], v[42:45], v[234:237], v[214:229]
	v_max_i32_e32 v248, 0, v9
	v_max_i32_e32 v249, 0, v1
	v_pk_fma_f32 v[184:185], v[100:101], v[246:247], 0 op_sel_hi:[1,1,0]
	v_pk_fma_f32 v[184:185], v[102:103], v[248:249], v[184:185]
	v_max_i32_e32 v246, 0, v10
	v_max_i32_e32 v247, 0, v2
	v_max_i32_e32 v248, 0, v11
	v_max_i32_e32 v249, 0, v3
	s_waitcnt lgkmcnt(4)
	v_mfma_f32_32x32x16_bf16 v[198:213], v[46:49], v[238:241], v[198:213]
	v_pk_fma_f32 v[184:185], v[104:105], v[246:247], v[184:185]
	v_pk_fma_f32 v[184:185], v[106:107], v[248:249], v[184:185]
	v_max_i32_e32 v246, 0, v12
	v_max_i32_e32 v247, 0, v4
	v_max_i32_e32 v248, 0, v13
	v_max_i32_e32 v249, 0, v5
	v_pk_fma_f32 v[184:185], v[108:109], v[246:247], v[184:185]
	v_pk_fma_f32 v[184:185], v[110:111], v[248:249], v[184:185]
	s_waitcnt lgkmcnt(3)
	v_mfma_f32_32x32x16_bf16 v[214:229], v[46:49], v[242:245], v[214:229]
	v_max_i32_e32 v246, 0, v14
	v_max_i32_e32 v247, 0, v6
	v_max_i32_e32 v248, 0, v15
	v_max_i32_e32 v249, 0, v7
	v_pk_fma_f32 v[184:185], v[112:113], v[246:247], v[184:185]
	v_pk_fma_f32 v[184:185], v[114:115], v[248:249], v[184:185]
	v_cmp_le_f32_e32 vcc, v250, v185
	s_mov_b64 s[52:53], vcc
	s_and_saveexec_b64 s[4:5], s[50:51]
	v_mov_b32_e32 v246, vcc_hi
	v_mov_b32_e32 v247, vcc_lo
	v_cndmask_b32_e64 v246, v246, v247, s[48:49]
	ds_write_b32 v162, v246 offset:20
	s_or_b64 exec, exec, s[4:5]
	v_cmp_le_f32_e32 vcc, v156, v185
	s_andn2_b64 vcc, vcc, s[52:53]
	s_cbranch_vccz .Lp2_skip11
	v_mov_b32_e32 v246, vcc_hi
	v_mov_b32_e32 v247, vcc_lo
	v_cndmask_b32_e64 v246, v246, v247, s[48:49]
	s_and_saveexec_b64 s[4:5], vcc
	s_cbranch_execz .Lp2_join11
	v_and_b32_e32 v247, v246, v127
	v_bcnt_u32_b32 v247, v247, v119
	v_cmp_gt_u32_e32 vcc, s35, v247
	s_and_b64 exec, exec, vcc
	s_cbranch_execz .Lp2_join11
	v_cmp_gt_f32_e64 s[52:53], 0, v185
	v_not_b32_e32 v248, v185
	s_nop 0
	v_cndmask_b32_e64 v33, -|v185|, v248, s[52:53]
	v_lshl_add_u64 v[154:155], v[88:89], 0, s[0:1]
	v_lshl_add_u64 v[154:155], v[154:155], 0, v[32:33]
	v_lshl_add_u32 v248, v247, 3, v160
	ds_write_b64 v248, v[154:155] offset:2048

.Lp2_skip11:
	v_cmp_le_f32_e32 vcc, v197, v184
	s_mov_b64 s[52:53], vcc
	s_and_saveexec_b64 s[4:5], s[50:51]
	v_mov_b32_e32 v246, vcc_hi
	v_mov_b32_e32 v247, vcc_lo
	v_cndmask_b32_e64 v246, v246, v247, s[48:49]
	ds_write_b32 v162, v246 offset:1044
	s_or_b64 exec, exec, s[4:5]
	v_cmp_le_f32_e32 vcc, v157, v184
	s_andn2_b64 vcc, vcc, s[52:53]
	s_cbranch_vccz .Lp2_skip12
	v_mov_b32_e32 v246, vcc_hi
	v_mov_b32_e32 v247, vcc_lo
	v_cndmask_b32_e64 v246, v246, v247, s[48:49]
	s_and_saveexec_b64 s[4:5], vcc
	s_cbranch_execz .Lp2_join12
	v_and_b32_e32 v247, v246, v127
	v_bcnt_u32_b32 v247, v247, v118
	v_cmp_gt_u32_e32 vcc, s35, v247
	s_and_b64 exec, exec, vcc
	s_cbranch_execz .Lp2_join12
	v_cmp_gt_f32_e64 s[52:53], 0, v184
	v_not_b32_e32 v248, v184
	s_nop 0
	v_cndmask_b32_e64 v33, -|v184|, v248, s[52:53]
	v_lshl_add_u64 v[154:155], v[88:89], 0, s[0:1]
	v_lshl_add_u64 v[154:155], v[154:155], 0, v[32:33]
	v_lshl_add_u32 v248, v247, 3, v161
	ds_write_b64 v248, v[154:155] offset:2048

.Lp2_c0:
	ds_read_b128 v[164:167], v99 offset:0
	ds_read_b128 v[168:171], v99 offset:4096
	ds_read_b128 v[172:175], v99 offset:1024
	ds_read_b128 v[176:179], v99 offset:5120
	ds_read_b128 v[230:233], v99 offset:2048
	ds_read_b128 v[234:237], v99 offset:6144
	ds_read_b128 v[238:241], v99 offset:3072
	ds_read_b128 v[242:245], v99 offset:7168
	v_max_i32_e32 v246, 0, v206
	v_max_i32_e32 v247, 0, v198
	v_max_i32_e32 v248, 0, v207
	v_max_i32_e32 v249, 0, v199
	s_waitcnt lgkmcnt(7)
	v_mfma_f32_32x32x16_bf16 v[16:31], v[34:37], v[164:167], 0
	v_pk_fma_f32 v[184:185], v[100:101], v[246:247], 0 op_sel_hi:[1,1,0]
	v_pk_fma_f32 v[184:185], v[102:103], v[248:249], v[184:185]
	v_max_i32_e32 v246, 0, v208
	v_max_i32_e32 v247, 0, v200
	v_max_i32_e32 v248, 0, v209
	v_max_i32_e32 v249, 0, v201
	v_pk_fma_f32 v[184:185], v[104:105], v[246:247], v[184:185]
	v_pk_fma_f32 v[184:185], v[106:107], v[248:249], v[184:185]
	s_waitcnt lgkmcnt(6)
	v_mfma_f32_32x32x16_bf16 v[0:15], v[34:37], v[168:171], 0
	s_waitcnt vmcnt(3)
	ds_write_b128 v140, v[50:53] offset:8192
	s_add_i32 s4, s18, 5
	s_min_i32 s4, s4, s14
	v_mad_i64_i32 v[164:165], s[4:5], s4, v193, v[116:117]
	global_load_dwordx4 v[50:53], v[164:165], off
	v_max_i32_e32 v246, 0, v210
	v_max_i32_e32 v247, 0, v202
	v_max_i32_e32 v248, 0, v211
	v_max_i32_e32 v249, 0, v203
	v_pk_fma_f32 v[184:185], v[108:109], v[246:247], v[184:185]
	v_pk_fma_f32 v[184:185], v[110:111], v[248:249], v[184:185]
	v_max_i32_e32 v246, 0, v212
	v_max_i32_e32 v247, 0, v204
	s_waitcnt lgkmcnt(6)
	v_mfma_f32_32x32x16_bf16 v[16:31], v[38:41], v[172:175], v[16:31]
	v_max_i32_e32 v248, 0, v213
	v_max_i32_e32 v249, 0, v205
	v_pk_fma_f32 v[184:185], v[112:113], v[246:247], v[184:185]
	v_pk_fma_f32 v[184:185], v[114:115], v[248:249], v[184:185]
	s_waitcnt lgkmcnt(5)
	v_mfma_f32_32x32x16_bf16 v[0:15], v[38:41], v[176:179], v[0:15]
	v_cmp_le_f32_e32 vcc, v250, v185
	s_mov_b64 s[52:53], vcc
	s_and_saveexec_b64 s[4:5], s[50:51]
	v_mov_b32_e32 v246, vcc_hi
	v_mov_b32_e32 v247, vcc_lo
	v_cndmask_b32_e64 v246, v246, v247, s[48:49]
	ds_write_b32 v162, v246 offset:24
	s_or_b64 exec, exec, s[4:5]
	v_cmp_le_f32_e32 vcc, v156, v185
	s_andn2_b64 vcc, vcc, s[52:53]
	s_cbranch_vccz .Lp2_skip13
	v_mov_b32_e32 v246, vcc_hi
	v_mov_b32_e32 v247, vcc_lo
	v_cndmask_b32_e64 v246, v246, v247, s[48:49]
	s_and_saveexec_b64 s[4:5], vcc
	s_cbranch_execz .Lp2_join13
	v_and_b32_e32 v247, v246, v127
	v_bcnt_u32_b32 v247, v247, v119
	v_cmp_gt_u32_e32 vcc, s35, v247
	s_and_b64 exec, exec, vcc
	s_cbranch_execz .Lp2_join13
	v_cmp_gt_f32_e64 s[52:53], 0, v185
	v_not_b32_e32 v248, v185
	s_nop 0
	v_cndmask_b32_e64 v33, -|v185|, v248, s[52:53]
	v_lshl_add_u64 v[154:155], v[86:87], 0, s[0:1]
	v_lshl_add_u64 v[154:155], v[154:155], 0, v[32:33]
	v_lshl_add_u32 v248, v247, 3, v160
	ds_write_b64 v248, v[154:155] offset:2048

.Lp2_skip13:
	s_waitcnt lgkmcnt(5)
	v_mfma_f32_32x32x16_bf16 v[16:31], v[42:45], v[230:233], v[16:31]
	v_cmp_le_f32_e32 vcc, v197, v184
	s_mov_b64 s[52:53], vcc
	s_and_saveexec_b64 s[4:5], s[50:51]
	v_mov_b32_e32 v246, vcc_hi
	v_mov_b32_e32 v247, vcc_lo
	v_cndmask_b32_e64 v246, v246, v247, s[48:49]
	ds_write_b32 v162, v246 offset:1048
	s_or_b64 exec, exec, s[4:5]
	v_cmp_le_f32_e32 vcc, v157, v184
	s_andn2_b64 vcc, vcc, s[52:53]
	s_cbranch_vccz .Lp2_skip14
	v_mov_b32_e32 v246, vcc_hi
	v_mov_b32_e32 v247, vcc_lo
	v_cndmask_b32_e64 v246, v246, v247, s[48:49]
	s_and_saveexec_b64 s[4:5], vcc
	s_cbranch_execz .Lp2_join14
	v_and_b32_e32 v247, v246, v127
	v_bcnt_u32_b32 v247, v247, v118
	v_cmp_gt_u32_e32 vcc, s35, v247
	s_and_b64 exec, exec, vcc
	s_cbranch_execz .Lp2_join14
	v_cmp_gt_f32_e64 s[52:53], 0, v184
	v_not_b32_e32 v248, v184
	s_nop 0
	v_cndmask_b32_e64 v33, -|v184|, v248, s[52:53]
	v_lshl_add_u64 v[154:155], v[86:87], 0, s[0:1]
	v_lshl_add_u64 v[154:155], v[154:155], 0, v[32:33]
	v_lshl_add_u32 v248, v247, 3, v161
	ds_write_b64 v248, v[154:155] offset:2048

.Lp2_skip14:
	v_max_i32_e32 v246, 0, v222
	v_max_i32_e32 v247, 0, v214
	s_waitcnt lgkmcnt(5)
	v_mfma_f32_32x32x16_bf16 v[0:15], v[42:45], v[234:237], v[0:15]
	v_max_i32_e32 v248, 0, v223
	v_max_i32_e32 v249, 0, v215
	v_pk_fma_f32 v[184:185], v[100:101], v[246:247], 0 op_sel_hi:[1,1,0]
	v_pk_fma_f32 v[184:185], v[102:103], v[248:249], v[184:185]
	v_max_i32_e32 v246, 0, v224
	v_max_i32_e32 v247, 0, v216
	v_max_i32_e32 v248, 0, v225
	v_max_i32_e32 v249, 0, v217
	s_waitcnt lgkmcnt(4)
	v_mfma_f32_32x32x16_bf16 v[16:31], v[46:49], v[238:241], v[16:31]
	v_pk_fma_f32 v[184:185], v[104:105], v[246:247], v[184:185]
	v_pk_fma_f32 v[184:185], v[106:107], v[248:249], v[184:185]
	v_max_i32_e32 v246, 0, v226
	v_max_i32_e32 v247, 0, v218
	v_max_i32_e32 v248, 0, v227
	v_max_i32_e32 v249, 0, v219
	v_pk_fma_f32 v[184:185], v[108:109], v[246:247], v[184:185]
	v_pk_fma_f32 v[184:185], v[110:111], v[248:249], v[184:185]
	s_waitcnt lgkmcnt(3)
	v_mfma_f32_32x32x16_bf16 v[0:15], v[46:49], v[242:245], v[0:15]
	v_max_i32_e32 v246, 0, v228
	v_max_i32_e32 v247, 0, v220
	v_max_i32_e32 v248, 0, v229
	v_max_i32_e32 v249, 0, v221
	v_pk_fma_f32 v[184:185], v[112:113], v[246:247], v[184:185]
	v_pk_fma_f32 v[184:185], v[114:115], v[248:249], v[184:185]
	v_cmp_le_f32_e32 vcc, v250, v185
	s_mov_b64 s[52:53], vcc
	s_and_saveexec_b64 s[4:5], s[50:51]
	v_mov_b32_e32 v246, vcc_hi
	v_mov_b32_e32 v247, vcc_lo
	v_cndmask_b32_e64 v246, v246, v247, s[48:49]
	ds_write_b32 v162, v246 offset:28
	s_or_b64 exec, exec, s[4:5]
	v_cmp_le_f32_e32 vcc, v156, v185
	s_andn2_b64 vcc, vcc, s[52:53]
	s_cbranch_vccz .Lp2_skip15
	v_mov_b32_e32 v246, vcc_hi
	v_mov_b32_e32 v247, vcc_lo
	v_cndmask_b32_e64 v246, v246, v247, s[48:49]
	s_and_saveexec_b64 s[4:5], vcc
	s_cbranch_execz .Lp2_join15
	v_and_b32_e32 v247, v246, v127
	v_bcnt_u32_b32 v247, v247, v119
	v_cmp_gt_u32_e32 vcc, s35, v247
	s_and_b64 exec, exec, vcc
	s_cbranch_execz .Lp2_join15
	v_cmp_gt_f32_e64 s[52:53], 0, v185
	v_not_b32_e32 v248, v185
	s_nop 0
	v_cndmask_b32_e64 v33, -|v185|, v248, s[52:53]
	v_lshl_add_u64 v[154:155], v[84:85], 0, s[0:1]
	v_lshl_add_u64 v[154:155], v[154:155], 0, v[32:33]
	v_lshl_add_u32 v248, v247, 3, v160
	ds_write_b64 v248, v[154:155] offset:2048

.Lp2_skip15:
	v_cmp_le_f32_e32 vcc, v197, v184
	s_mov_b64 s[52:53], vcc
	s_and_saveexec_b64 s[4:5], s[50:51]
	v_mov_b32_e32 v246, vcc_hi
	v_mov_b32_e32 v247, vcc_lo
	v_cndmask_b32_e64 v246, v246, v247, s[48:49]
	ds_write_b32 v162, v246 offset:1052
	s_or_b64 exec, exec, s[4:5]
	v_cmp_le_f32_e32 vcc, v157, v184
	s_andn2_b64 vcc, vcc, s[52:53]
	s_cbranch_vccz .Lp2_skip16
	v_mov_b32_e32 v246, vcc_hi
	v_mov_b32_e32 v247, vcc_lo
	v_cndmask_b32_e64 v246, v246, v247, s[48:49]
	s_and_saveexec_b64 s[4:5], vcc
	s_cbranch_execz .Lp2_join16
	v_and_b32_e32 v247, v246, v127
	v_bcnt_u32_b32 v247, v247, v118
	v_cmp_gt_u32_e32 vcc, s35, v247
	s_and_b64 exec, exec, vcc
	s_cbranch_execz .Lp2_join16
	v_cmp_gt_f32_e64 s[52:53], 0, v184
	v_not_b32_e32 v248, v184
	s_nop 0
	v_cndmask_b32_e64 v33, -|v184|, v248, s[52:53]
	v_lshl_add_u64 v[154:155], v[84:85], 0, s[0:1]
	v_lshl_add_u64 v[154:155], v[154:155], 0, v[32:33]
	v_lshl_add_u32 v248, v247, 3, v161
	ds_write_b64 v248, v[154:155] offset:2048

.Lp2_drain0:
	v_max_i32_e32 v246, 0, v24
	v_max_i32_e32 v247, 0, v16
	v_max_i32_e32 v248, 0, v25
	v_max_i32_e32 v249, 0, v17
	v_pk_fma_f32 v[184:185], v[100:101], v[246:247], 0 op_sel_hi:[1,1,0]
	v_pk_fma_f32 v[184:185], v[102:103], v[248:249], v[184:185]
	v_max_i32_e32 v246, 0, v26
	v_max_i32_e32 v247, 0, v18
	v_max_i32_e32 v248, 0, v27
	v_max_i32_e32 v249, 0, v19
	v_pk_fma_f32 v[184:185], v[104:105], v[246:247], v[184:185]
	v_pk_fma_f32 v[184:185], v[106:107], v[248:249], v[184:185]
	v_max_i32_e32 v246, 0, v28
	v_max_i32_e32 v247, 0, v20
	v_max_i32_e32 v248, 0, v29
	v_max_i32_e32 v249, 0, v21
	v_pk_fma_f32 v[184:185], v[108:109], v[246:247], v[184:185]
	v_pk_fma_f32 v[184:185], v[110:111], v[248:249], v[184:185]
	v_max_i32_e32 v246, 0, v30
	v_max_i32_e32 v247, 0, v22
	v_max_i32_e32 v248, 0, v31
	v_max_i32_e32 v249, 0, v23
	v_pk_fma_f32 v[184:185], v[112:113], v[246:247], v[184:185]
	v_pk_fma_f32 v[184:185], v[114:115], v[248:249], v[184:185]
	v_cmp_le_f32_e32 vcc, v250, v185
	s_mov_b64 s[52:53], vcc
	s_and_saveexec_b64 s[4:5], s[50:51]
	v_mov_b32_e32 v246, vcc_hi
	v_mov_b32_e32 v247, vcc_lo
	v_cndmask_b32_e64 v246, v246, v247, s[48:49]
	ds_write_b32 v162, v246
	s_or_b64 exec, exec, s[4:5]
	v_cmp_le_f32_e32 vcc, v156, v185
	s_andn2_b64 vcc, vcc, s[52:53]
	s_cbranch_vccz .Lp2_skip17
	v_mov_b32_e32 v246, vcc_hi
	v_mov_b32_e32 v247, vcc_lo
	v_cndmask_b32_e64 v246, v246, v247, s[48:49]
	s_and_saveexec_b64 s[4:5], vcc
	s_cbranch_execz .Lp2_join17
	v_and_b32_e32 v247, v246, v127
	v_bcnt_u32_b32 v247, v247, v119
	v_cmp_gt_u32_e32 vcc, s35, v247
	s_and_b64 exec, exec, vcc
	s_cbranch_execz .Lp2_join17
	v_cmp_gt_f32_e64 s[52:53], 0, v185
	v_not_b32_e32 v248, v185
	s_nop 0
	v_cndmask_b32_e64 v33, -|v185|, v248, s[52:53]
	v_lshl_add_u64 v[154:155], v[78:79], 0, s[0:1]
	v_lshl_add_u64 v[154:155], v[154:155], 0, v[32:33]
	v_lshl_add_u32 v248, v247, 3, v160
	ds_write_b64 v248, v[154:155] offset:2048

.Lp2_skip17:
	v_cmp_le_f32_e32 vcc, v197, v184
	s_mov_b64 s[52:53], vcc
	s_and_saveexec_b64 s[4:5], s[50:51]
	v_mov_b32_e32 v246, vcc_hi
	v_mov_b32_e32 v247, vcc_lo
	v_cndmask_b32_e64 v246, v246, v247, s[48:49]
	ds_write_b32 v162, v246 offset:1024
	s_or_b64 exec, exec, s[4:5]
	v_cmp_le_f32_e32 vcc, v157, v184
	s_andn2_b64 vcc, vcc, s[52:53]
	s_cbranch_vccz .Lp2_skip18
	v_mov_b32_e32 v246, vcc_hi
	v_mov_b32_e32 v247, vcc_lo
	v_cndmask_b32_e64 v246, v246, v247, s[48:49]
	s_and_saveexec_b64 s[4:5], vcc
	s_cbranch_execz .Lp2_join18
	v_and_b32_e32 v247, v246, v127
	v_bcnt_u32_b32 v247, v247, v118
	v_cmp_gt_u32_e32 vcc, s35, v247
	s_and_b64 exec, exec, vcc
	s_cbranch_execz .Lp2_join18
	v_cmp_gt_f32_e64 s[52:53], 0, v184
	v_not_b32_e32 v248, v184
	s_nop 0
	v_cndmask_b32_e64 v33, -|v184|, v248, s[52:53]
	v_lshl_add_u64 v[154:155], v[78:79], 0, s[0:1]
	v_lshl_add_u64 v[154:155], v[154:155], 0, v[32:33]
	v_lshl_add_u32 v248, v247, 3, v161
	ds_write_b64 v248, v[154:155] offset:2048

.Lp2_skip18:
	v_max_i32_e32 v246, 0, v8
	v_max_i32_e32 v247, 0, v0
	v_max_i32_e32 v248, 0, v9
	v_max_i32_e32 v249, 0, v1
	v_pk_fma_f32 v[184:185], v[100:101], v[246:247], 0 op_sel_hi:[1,1,0]
	v_pk_fma_f32 v[184:185], v[102:103], v[248:249], v[184:185]
	v_max_i32_e32 v246, 0, v10
	v_max_i32_e32 v247, 0, v2
	v_max_i32_e32 v248, 0, v11
	v_max_i32_e32 v249, 0, v3
	v_pk_fma_f32 v[184:185], v[104:105], v[246:247], v[184:185]
	v_pk_fma_f32 v[184:185], v[106:107], v[248:249], v[184:185]
	v_max_i32_e32 v246, 0, v12
	v_max_i32_e32 v247, 0, v4
	v_max_i32_e32 v248, 0, v13
	v_max_i32_e32 v249, 0, v5
	v_pk_fma_f32 v[184:185], v[108:109], v[246:247], v[184:185]
	v_pk_fma_f32 v[184:185], v[110:111], v[248:249], v[184:185]
	v_max_i32_e32 v246, 0, v14
	v_max_i32_e32 v247, 0, v6
	v_max_i32_e32 v248, 0, v15
	v_max_i32_e32 v249, 0, v7
	v_pk_fma_f32 v[184:185], v[112:113], v[246:247], v[184:185]
	v_pk_fma_f32 v[184:185], v[114:115], v[248:249], v[184:185]
	v_cmp_le_f32_e32 vcc, v250, v185
	s_mov_b64 s[52:53], vcc
	s_and_saveexec_b64 s[4:5], s[50:51]
	v_mov_b32_e32 v246, vcc_hi
	v_mov_b32_e32 v247, vcc_lo
	v_cndmask_b32_e64 v246, v246, v247, s[48:49]
	ds_write_b32 v162, v246 offset:4
	s_or_b64 exec, exec, s[4:5]
	v_cmp_le_f32_e32 vcc, v156, v185
	s_andn2_b64 vcc, vcc, s[52:53]
	s_cbranch_vccz .Lp2_skip19
	v_mov_b32_e32 v246, vcc_hi
	v_mov_b32_e32 v247, vcc_lo
	v_cndmask_b32_e64 v246, v246, v247, s[48:49]
	s_and_saveexec_b64 s[4:5], vcc
	s_cbranch_execz .Lp2_join19
	v_and_b32_e32 v247, v246, v127
	v_bcnt_u32_b32 v247, v247, v119
	v_cmp_gt_u32_e32 vcc, s35, v247
	s_and_b64 exec, exec, vcc
	s_cbranch_execz .Lp2_join19
	v_cmp_gt_f32_e64 s[52:53], 0, v185
	v_not_b32_e32 v248, v185
	s_nop 0
	v_cndmask_b32_e64 v33, -|v185|, v248, s[52:53]
	v_lshl_add_u64 v[154:155], v[96:97], 0, s[0:1]
	v_lshl_add_u64 v[154:155], v[154:155], 0, v[32:33]
	v_lshl_add_u32 v248, v247, 3, v160
	ds_write_b64 v248, v[154:155] offset:2048

.Lp2_drain1:
	v_max_i32_e32 v246, 0, v206
	v_max_i32_e32 v247, 0, v198
	v_max_i32_e32 v248, 0, v207
	v_max_i32_e32 v249, 0, v199
	v_pk_fma_f32 v[184:185], v[100:101], v[246:247], 0 op_sel_hi:[1,1,0]
	v_pk_fma_f32 v[184:185], v[102:103], v[248:249], v[184:185]
	v_max_i32_e32 v246, 0, v208
	v_max_i32_e32 v247, 0, v200
	v_max_i32_e32 v248, 0, v209
	v_max_i32_e32 v249, 0, v201
	v_pk_fma_f32 v[184:185], v[104:105], v[246:247], v[184:185]
	v_pk_fma_f32 v[184:185], v[106:107], v[248:249], v[184:185]
	v_max_i32_e32 v246, 0, v210
	v_max_i32_e32 v247, 0, v202
	v_max_i32_e32 v248, 0, v211
	v_max_i32_e32 v249, 0, v203
	v_pk_fma_f32 v[184:185], v[108:109], v[246:247], v[184:185]
	v_pk_fma_f32 v[184:185], v[110:111], v[248:249], v[184:185]
	v_max_i32_e32 v246, 0, v212
	v_max_i32_e32 v247, 0, v204
	v_max_i32_e32 v248, 0, v213
	v_max_i32_e32 v249, 0, v205
	v_pk_fma_f32 v[184:185], v[112:113], v[246:247], v[184:185]
	v_pk_fma_f32 v[184:185], v[114:115], v[248:249], v[184:185]
	v_cmp_le_f32_e32 vcc, v250, v185
	s_mov_b64 s[52:53], vcc
	s_and_saveexec_b64 s[4:5], s[50:51]
	v_mov_b32_e32 v246, vcc_hi
	v_mov_b32_e32 v247, vcc_lo
	v_cndmask_b32_e64 v246, v246, v247, s[48:49]
	ds_write_b32 v162, v246 offset:8
	s_or_b64 exec, exec, s[4:5]
	v_cmp_le_f32_e32 vcc, v156, v185
	s_andn2_b64 vcc, vcc, s[52:53]
	s_cbranch_vccz .Lp2_skip21
	v_mov_b32_e32 v246, vcc_hi
	v_mov_b32_e32 v247, vcc_lo
	v_cndmask_b32_e64 v246, v246, v247, s[48:49]
	s_and_saveexec_b64 s[4:5], vcc
	s_cbranch_execz .Lp2_join21
	v_and_b32_e32 v247, v246, v127
	v_bcnt_u32_b32 v247, v247, v119
	v_cmp_gt_u32_e32 vcc, s35, v247
	s_and_b64 exec, exec, vcc
	s_cbranch_execz .Lp2_join21
	v_cmp_gt_f32_e64 s[52:53], 0, v185
	v_not_b32_e32 v248, v185
	s_nop 0
	v_cndmask_b32_e64 v33, -|v185|, v248, s[52:53]
	v_lshl_add_u64 v[154:155], v[92:93], 0, s[0:1]
	v_lshl_add_u64 v[154:155], v[154:155], 0, v[32:33]
	v_lshl_add_u32 v248, v247, 3, v160
	ds_write_b64 v248, v[154:155] offset:2048

.Lp2_skip21:
	v_cmp_le_f32_e32 vcc, v197, v184
	s_mov_b64 s[52:53], vcc
	s_and_saveexec_b64 s[4:5], s[50:51]
	v_mov_b32_e32 v246, vcc_hi
	v_mov_b32_e32 v247, vcc_lo
	v_cndmask_b32_e64 v246, v246, v247, s[48:49]
	ds_write_b32 v162, v246 offset:1032
	s_or_b64 exec, exec, s[4:5]
	v_cmp_le_f32_e32 vcc, v157, v184
	s_andn2_b64 vcc, vcc, s[52:53]
	s_cbranch_vccz .Lp2_skip22
	v_mov_b32_e32 v246, vcc_hi
	v_mov_b32_e32 v247, vcc_lo
	v_cndmask_b32_e64 v246, v246, v247, s[48:49]
	s_and_saveexec_b64 s[4:5], vcc
	s_cbranch_execz .Lp2_join22
	v_and_b32_e32 v247, v246, v127
	v_bcnt_u32_b32 v247, v247, v118
	v_cmp_gt_u32_e32 vcc, s35, v247
	s_and_b64 exec, exec, vcc
	s_cbranch_execz .Lp2_join22
	v_cmp_gt_f32_e64 s[52:53], 0, v184
	v_not_b32_e32 v248, v184
	s_nop 0
	v_cndmask_b32_e64 v33, -|v184|, v248, s[52:53]
	v_lshl_add_u64 v[154:155], v[92:93], 0, s[0:1]
	v_lshl_add_u64 v[154:155], v[154:155], 0, v[32:33]
	v_lshl_add_u32 v248, v247, 3, v161
	ds_write_b64 v248, v[154:155] offset:2048

.Lp2_skip22:
	v_max_i32_e32 v246, 0, v222
	v_max_i32_e32 v247, 0, v214
	v_max_i32_e32 v248, 0, v223
	v_max_i32_e32 v249, 0, v215
	v_pk_fma_f32 v[184:185], v[100:101], v[246:247], 0 op_sel_hi:[1,1,0]
	v_pk_fma_f32 v[184:185], v[102:103], v[248:249], v[184:185]
	v_max_i32_e32 v246, 0, v224
	v_max_i32_e32 v247, 0, v216
	v_max_i32_e32 v248, 0, v225
	v_max_i32_e32 v249, 0, v217
	v_pk_fma_f32 v[184:185], v[104:105], v[246:247], v[184:185]
	v_pk_fma_f32 v[184:185], v[106:107], v[248:249], v[184:185]
	v_max_i32_e32 v246, 0, v226
	v_max_i32_e32 v247, 0, v218
	v_max_i32_e32 v248, 0, v227
	v_max_i32_e32 v249, 0, v219
	v_pk_fma_f32 v[184:185], v[108:109], v[246:247], v[184:185]
	v_pk_fma_f32 v[184:185], v[110:111], v[248:249], v[184:185]
	v_max_i32_e32 v246, 0, v228
	v_max_i32_e32 v247, 0, v220
	v_max_i32_e32 v248, 0, v229
	v_max_i32_e32 v249, 0, v221
	v_pk_fma_f32 v[184:185], v[112:113], v[246:247], v[184:185]
	v_pk_fma_f32 v[184:185], v[114:115], v[248:249], v[184:185]
	v_cmp_le_f32_e32 vcc, v250, v185
	s_mov_b64 s[52:53], vcc
	s_and_saveexec_b64 s[4:5], s[50:51]
	v_mov_b32_e32 v246, vcc_hi
	v_mov_b32_e32 v247, vcc_lo
	v_cndmask_b32_e64 v246, v246, v247, s[48:49]
	ds_write_b32 v162, v246 offset:12
	s_or_b64 exec, exec, s[4:5]
	v_cmp_le_f32_e32 vcc, v156, v185
	s_andn2_b64 vcc, vcc, s[52:53]
	s_cbranch_vccz .Lp2_skip23
	v_mov_b32_e32 v246, vcc_hi
	v_mov_b32_e32 v247, vcc_lo
	v_cndmask_b32_e64 v246, v246, v247, s[48:49]
	s_and_saveexec_b64 s[4:5], vcc
	s_cbranch_execz .Lp2_join23
	v_and_b32_e32 v247, v246, v127
	v_bcnt_u32_b32 v247, v247, v119
	v_cmp_gt_u32_e32 vcc, s35, v247
	s_and_b64 exec, exec, vcc
	s_cbranch_execz .Lp2_join23
	v_cmp_gt_f32_e64 s[52:53], 0, v185
	v_not_b32_e32 v248, v185
	s_nop 0
	v_cndmask_b32_e64 v33, -|v185|, v248, s[52:53]
	v_lshl_add_u64 v[154:155], v[94:95], 0, s[0:1]
	v_lshl_add_u64 v[154:155], v[154:155], 0, v[32:33]
	v_lshl_add_u32 v248, v247, 3, v160
	ds_write_b64 v248, v[154:155] offset:2048

.Lp2_drain2:
	v_max_i32_e32 v246, 0, v24
	v_max_i32_e32 v247, 0, v16
	v_max_i32_e32 v248, 0, v25
	v_max_i32_e32 v249, 0, v17
	v_pk_fma_f32 v[184:185], v[100:101], v[246:247], 0 op_sel_hi:[1,1,0]
	v_pk_fma_f32 v[184:185], v[102:103], v[248:249], v[184:185]
	v_max_i32_e32 v246, 0, v26
	v_max_i32_e32 v247, 0, v18
	v_max_i32_e32 v248, 0, v27
	v_max_i32_e32 v249, 0, v19
	v_pk_fma_f32 v[184:185], v[104:105], v[246:247], v[184:185]
	v_pk_fma_f32 v[184:185], v[106:107], v[248:249], v[184:185]
	v_max_i32_e32 v246, 0, v28
	v_max_i32_e32 v247, 0, v20
	v_max_i32_e32 v248, 0, v29
	v_max_i32_e32 v249, 0, v21
	v_pk_fma_f32 v[184:185], v[108:109], v[246:247], v[184:185]
	v_pk_fma_f32 v[184:185], v[110:111], v[248:249], v[184:185]
	v_max_i32_e32 v246, 0, v30
	v_max_i32_e32 v247, 0, v22
	v_max_i32_e32 v248, 0, v31
	v_max_i32_e32 v249, 0, v23
	v_pk_fma_f32 v[184:185], v[112:113], v[246:247], v[184:185]
	v_pk_fma_f32 v[184:185], v[114:115], v[248:249], v[184:185]
	v_cmp_le_f32_e32 vcc, v250, v185
	s_mov_b64 s[52:53], vcc
	s_and_saveexec_b64 s[4:5], s[50:51]
	v_mov_b32_e32 v246, vcc_hi
	v_mov_b32_e32 v247, vcc_lo
	v_cndmask_b32_e64 v246, v246, v247, s[48:49]
	ds_write_b32 v162, v246 offset:16
	s_or_b64 exec, exec, s[4:5]
	v_cmp_le_f32_e32 vcc, v156, v185
	s_andn2_b64 vcc, vcc, s[52:53]
	s_cbranch_vccz .Lp2_skip25
	v_mov_b32_e32 v246, vcc_hi
	v_mov_b32_e32 v247, vcc_lo
	v_cndmask_b32_e64 v246, v246, v247, s[48:49]
	s_and_saveexec_b64 s[4:5], vcc
	s_cbranch_execz .Lp2_join25
	v_and_b32_e32 v247, v246, v127
	v_bcnt_u32_b32 v247, v247, v119
	v_cmp_gt_u32_e32 vcc, s35, v247
	s_and_b64 exec, exec, vcc
	s_cbranch_execz .Lp2_join25
	v_cmp_gt_f32_e64 s[52:53], 0, v185
	v_not_b32_e32 v248, v185
	s_nop 0
	v_cndmask_b32_e64 v33, -|v185|, v248, s[52:53]
	v_lshl_add_u64 v[154:155], v[90:91], 0, s[0:1]
	v_lshl_add_u64 v[154:155], v[154:155], 0, v[32:33]
	v_lshl_add_u32 v248, v247, 3, v160
	ds_write_b64 v248, v[154:155] offset:2048

.Lp2_skip25:
	v_cmp_le_f32_e32 vcc, v197, v184
	s_mov_b64 s[52:53], vcc
	s_and_saveexec_b64 s[4:5], s[50:51]
	v_mov_b32_e32 v246, vcc_hi
	v_mov_b32_e32 v247, vcc_lo
	v_cndmask_b32_e64 v246, v246, v247, s[48:49]
	ds_write_b32 v162, v246 offset:1040
	s_or_b64 exec, exec, s[4:5]
	v_cmp_le_f32_e32 vcc, v157, v184
	s_andn2_b64 vcc, vcc, s[52:53]
	s_cbranch_vccz .Lp2_skip26
	v_mov_b32_e32 v246, vcc_hi
	v_mov_b32_e32 v247, vcc_lo
	v_cndmask_b32_e64 v246, v246, v247, s[48:49]
	s_and_saveexec_b64 s[4:5], vcc
	s_cbranch_execz .Lp2_join26
	v_and_b32_e32 v247, v246, v127
	v_bcnt_u32_b32 v247, v247, v118
	v_cmp_gt_u32_e32 vcc, s35, v247
	s_and_b64 exec, exec, vcc
	s_cbranch_execz .Lp2_join26
	v_cmp_gt_f32_e64 s[52:53], 0, v184
	v_not_b32_e32 v248, v184
	s_nop 0
	v_cndmask_b32_e64 v33, -|v184|, v248, s[52:53]
	v_lshl_add_u64 v[154:155], v[90:91], 0, s[0:1]
	v_lshl_add_u64 v[154:155], v[154:155], 0, v[32:33]
	v_lshl_add_u32 v248, v247, 3, v161
	ds_write_b64 v248, v[154:155] offset:2048

.Lp2_skip26:
	v_max_i32_e32 v246, 0, v8
	v_max_i32_e32 v247, 0, v0
	v_max_i32_e32 v248, 0, v9
	v_max_i32_e32 v249, 0, v1
	v_pk_fma_f32 v[184:185], v[100:101], v[246:247], 0 op_sel_hi:[1,1,0]
	v_pk_fma_f32 v[184:185], v[102:103], v[248:249], v[184:185]
	v_max_i32_e32 v246, 0, v10
	v_max_i32_e32 v247, 0, v2
	v_max_i32_e32 v248, 0, v11
	v_max_i32_e32 v249, 0, v3
	v_pk_fma_f32 v[184:185], v[104:105], v[246:247], v[184:185]
	v_pk_fma_f32 v[184:185], v[106:107], v[248:249], v[184:185]
	v_max_i32_e32 v246, 0, v12
	v_max_i32_e32 v247, 0, v4
	v_max_i32_e32 v248, 0, v13
	v_max_i32_e32 v249, 0, v5
	v_pk_fma_f32 v[184:185], v[108:109], v[246:247], v[184:185]
	v_pk_fma_f32 v[184:185], v[110:111], v[248:249], v[184:185]
	v_max_i32_e32 v246, 0, v14
	v_max_i32_e32 v247, 0, v6
	v_max_i32_e32 v248, 0, v15
	v_max_i32_e32 v249, 0, v7
	v_pk_fma_f32 v[184:185], v[112:113], v[246:247], v[184:185]
	v_pk_fma_f32 v[184:185], v[114:115], v[248:249], v[184:185]
	v_cmp_le_f32_e32 vcc, v250, v185
	s_mov_b64 s[52:53], vcc
	s_and_saveexec_b64 s[4:5], s[50:51]
	v_mov_b32_e32 v246, vcc_hi
	v_mov_b32_e32 v247, vcc_lo
	v_cndmask_b32_e64 v246, v246, v247, s[48:49]
	ds_write_b32 v162, v246 offset:20
	s_or_b64 exec, exec, s[4:5]
	v_cmp_le_f32_e32 vcc, v156, v185
	s_andn2_b64 vcc, vcc, s[52:53]
	s_cbranch_vccz .Lp2_skip27
	v_mov_b32_e32 v246, vcc_hi
	v_mov_b32_e32 v247, vcc_lo
	v_cndmask_b32_e64 v246, v246, v247, s[48:49]
	s_and_saveexec_b64 s[4:5], vcc
	s_cbranch_execz .Lp2_join27
	v_and_b32_e32 v247, v246, v127
	v_bcnt_u32_b32 v247, v247, v119
	v_cmp_gt_u32_e32 vcc, s35, v247
	s_and_b64 exec, exec, vcc
	s_cbranch_execz .Lp2_join27
	v_cmp_gt_f32_e64 s[52:53], 0, v185
	v_not_b32_e32 v248, v185
	s_nop 0
	v_cndmask_b32_e64 v33, -|v185|, v248, s[52:53]
	v_lshl_add_u64 v[154:155], v[88:89], 0, s[0:1]
	v_lshl_add_u64 v[154:155], v[154:155], 0, v[32:33]
	v_lshl_add_u32 v248, v247, 3, v160
	ds_write_b64 v248, v[154:155] offset:2048

.Lp2_drain3:
	v_max_i32_e32 v246, 0, v206
	v_max_i32_e32 v247, 0, v198
	v_max_i32_e32 v248, 0, v207
	v_max_i32_e32 v249, 0, v199
	v_pk_fma_f32 v[184:185], v[100:101], v[246:247], 0 op_sel_hi:[1,1,0]
	v_pk_fma_f32 v[184:185], v[102:103], v[248:249], v[184:185]
	v_max_i32_e32 v246, 0, v208
	v_max_i32_e32 v247, 0, v200
	v_max_i32_e32 v248, 0, v209
	v_max_i32_e32 v249, 0, v201
	v_pk_fma_f32 v[184:185], v[104:105], v[246:247], v[184:185]
	v_pk_fma_f32 v[184:185], v[106:107], v[248:249], v[184:185]
	v_max_i32_e32 v246, 0, v210
	v_max_i32_e32 v247, 0, v202
	v_max_i32_e32 v248, 0, v211
	v_max_i32_e32 v249, 0, v203
	v_pk_fma_f32 v[184:185], v[108:109], v[246:247], v[184:185]
	v_pk_fma_f32 v[184:185], v[110:111], v[248:249], v[184:185]
	v_max_i32_e32 v246, 0, v212
	v_max_i32_e32 v247, 0, v204
	v_max_i32_e32 v248, 0, v213
	v_max_i32_e32 v249, 0, v205
	v_pk_fma_f32 v[184:185], v[112:113], v[246:247], v[184:185]
	v_pk_fma_f32 v[184:185], v[114:115], v[248:249], v[184:185]
	v_cmp_le_f32_e32 vcc, v250, v185
	s_mov_b64 s[52:53], vcc
	s_and_saveexec_b64 s[4:5], s[50:51]
	v_mov_b32_e32 v246, vcc_hi
	v_mov_b32_e32 v247, vcc_lo
	v_cndmask_b32_e64 v246, v246, v247, s[48:49]
	ds_write_b32 v162, v246 offset:24
	s_or_b64 exec, exec, s[4:5]
	v_cmp_le_f32_e32 vcc, v156, v185
	s_andn2_b64 vcc, vcc, s[52:53]
	s_cbranch_vccz .Lp2_skip29
	v_mov_b32_e32 v246, vcc_hi
	v_mov_b32_e32 v247, vcc_lo
	v_cndmask_b32_e64 v246, v246, v247, s[48:49]
	s_and_saveexec_b64 s[4:5], vcc
	s_cbranch_execz .Lp2_join29
	v_and_b32_e32 v247, v246, v127
	v_bcnt_u32_b32 v247, v247, v119
	v_cmp_gt_u32_e32 vcc, s35, v247
	s_and_b64 exec, exec, vcc
	s_cbranch_execz .Lp2_join29
	v_cmp_gt_f32_e64 s[52:53], 0, v185
	v_not_b32_e32 v248, v185
	s_nop 0
	v_cndmask_b32_e64 v33, -|v185|, v248, s[52:53]
	v_lshl_add_u64 v[154:155], v[86:87], 0, s[0:1]
	v_lshl_add_u64 v[154:155], v[154:155], 0, v[32:33]
	v_lshl_add_u32 v248, v247, 3, v160
	ds_write_b64 v248, v[154:155] offset:2048

.Lp2_skip29:
	v_cmp_le_f32_e32 vcc, v197, v184
	s_mov_b64 s[52:53], vcc
	s_and_saveexec_b64 s[4:5], s[50:51]
	v_mov_b32_e32 v246, vcc_hi
	v_mov_b32_e32 v247, vcc_lo
	v_cndmask_b32_e64 v246, v246, v247, s[48:49]
	ds_write_b32 v162, v246 offset:1048
	s_or_b64 exec, exec, s[4:5]
	v_cmp_le_f32_e32 vcc, v157, v184
	s_andn2_b64 vcc, vcc, s[52:53]
	s_cbranch_vccz .Lp2_skip30
	v_mov_b32_e32 v246, vcc_hi
	v_mov_b32_e32 v247, vcc_lo
	v_cndmask_b32_e64 v246, v246, v247, s[48:49]
	s_and_saveexec_b64 s[4:5], vcc
	s_cbranch_execz .Lp2_join30
	v_and_b32_e32 v247, v246, v127
	v_bcnt_u32_b32 v247, v247, v118
	v_cmp_gt_u32_e32 vcc, s35, v247
	s_and_b64 exec, exec, vcc
	s_cbranch_execz .Lp2_join30
	v_cmp_gt_f32_e64 s[52:53], 0, v184
	v_not_b32_e32 v248, v184
	s_nop 0
	v_cndmask_b32_e64 v33, -|v184|, v248, s[52:53]
	v_lshl_add_u64 v[154:155], v[86:87], 0, s[0:1]
	v_lshl_add_u64 v[154:155], v[154:155], 0, v[32:33]
	v_lshl_add_u32 v248, v247, 3, v161
	ds_write_b64 v248, v[154:155] offset:2048

.Lp2_skip30:
	v_max_i32_e32 v246, 0, v222
	v_max_i32_e32 v247, 0, v214
	v_max_i32_e32 v248, 0, v223
	v_max_i32_e32 v249, 0, v215
	v_pk_fma_f32 v[184:185], v[100:101], v[246:247], 0 op_sel_hi:[1,1,0]
	v_pk_fma_f32 v[184:185], v[102:103], v[248:249], v[184:185]
	v_max_i32_e32 v246, 0, v224
	v_max_i32_e32 v247, 0, v216
	v_max_i32_e32 v248, 0, v225
	v_max_i32_e32 v249, 0, v217
	v_pk_fma_f32 v[184:185], v[104:105], v[246:247], v[184:185]
	v_pk_fma_f32 v[184:185], v[106:107], v[248:249], v[184:185]
	v_max_i32_e32 v246, 0, v226
	v_max_i32_e32 v247, 0, v218
	v_max_i32_e32 v248, 0, v227
	v_max_i32_e32 v249, 0, v219
	v_pk_fma_f32 v[184:185], v[108:109], v[246:247], v[184:185]
	v_pk_fma_f32 v[184:185], v[110:111], v[248:249], v[184:185]
	v_max_i32_e32 v246, 0, v228
	v_max_i32_e32 v247, 0, v220
	v_max_i32_e32 v248, 0, v229
	v_max_i32_e32 v249, 0, v221
	v_pk_fma_f32 v[184:185], v[112:113], v[246:247], v[184:185]
	v_pk_fma_f32 v[184:185], v[114:115], v[248:249], v[184:185]
	v_cmp_le_f32_e32 vcc, v250, v185
	s_mov_b64 s[52:53], vcc
	s_and_saveexec_b64 s[4:5], s[50:51]
	v_mov_b32_e32 v246, vcc_hi
	v_mov_b32_e32 v247, vcc_lo
	v_cndmask_b32_e64 v246, v246, v247, s[48:49]
	ds_write_b32 v162, v246 offset:28
	s_or_b64 exec, exec, s[4:5]
	v_cmp_le_f32_e32 vcc, v156, v185
	s_andn2_b64 vcc, vcc, s[52:53]
	s_cbranch_vccz .Lp2_skip31
	v_mov_b32_e32 v246, vcc_hi
	v_mov_b32_e32 v247, vcc_lo
	v_cndmask_b32_e64 v246, v246, v247, s[48:49]
	s_and_saveexec_b64 s[4:5], vcc
	s_cbranch_execz .Lp2_join31
	v_and_b32_e32 v247, v246, v127
	v_bcnt_u32_b32 v247, v247, v119
	v_cmp_gt_u32_e32 vcc, s35, v247
	s_and_b64 exec, exec, vcc
	s_cbranch_execz .Lp2_join31
	v_cmp_gt_f32_e64 s[52:53], 0, v185
	v_not_b32_e32 v248, v185
	s_nop 0
	v_cndmask_b32_e64 v33, -|v185|, v248, s[52:53]
	v_lshl_add_u64 v[154:155], v[84:85], 0, s[0:1]
	v_lshl_add_u64 v[154:155], v[154:155], 0, v[32:33]
	v_lshl_add_u32 v248, v247, 3, v160
	ds_write_b64 v248, v[154:155] offset:2048
